# od / mlp row-norm passes: gain quads loaded once before the row loop instead of re-loaded behind vmcnt(0) three times per row; slab fold through a ring of destination quads
# speedup vs baseline: 1.0050x; 1.0050x over previous
; DEVI unsigned pk_bf16(float lo, float hi) { unsigned r; asm("v_cvt_pk_bf16_f32 %0, %1, %2" : "=v"(r) : "v"(lo), "v"(hi)); return r; }
; DEVI float wave_sum(float v) { for (int o = 32; o; o >>= 1) v += __shfl_xor(v, o); return v; }
; __device__ __forceinline__ void norm_phase(const Params& p, const float* __restrict__ gain, int mode, int nslab) {
;     ...
;   if (wave < M) { const float* src = srcrow(wave);
; #pragma unroll
;     for (int i = 0; i < 4; ++i) vn[i] = *(const float4*)(src + i * 256 + lane * 4); }
;   for (int r = wave; r < M; r += nw) {
;     float* hp = hrow(p, r);
; #pragma unroll
;     for (int i = 0; i < 4; ++i) v[i] = vn[i];
;     if (r + nw < M) { const float* src = srcrow(r + nw);
; #pragma unroll
;       for (int i = 0; i < 4; ++i) vn[i] = *(const float4*)(src + i * 256 + lane * 4); }
;     if (nslab > 0 && r >= 32768) {
;       const float* sl = (const float*)(p.ws + OFF_SLAB) + (size_t)(r - 32768) * 1024 + lane * 4;
;       for (int sI = 0; sI < nslab; ++sI)
; #pragma unroll
;         for (int i = 0; i < 4; ++i) { const float4 a = *(const float4*)(sl + (size_t)sI * 131072 + i * 256); v[i].x += a.x; v[i].y += a.y; v[i].z += a.z; v[i].w += a.w; }
; #pragma unroll
;       for (int i = 0; i < 4; ++i) *(float4*)(hp + i * 256 + lane * 4) = v[i];
;     }
;     float ss = 0.f;
; #pragma unroll
;     for (int i = 0; i < 4; ++i) ss += v[i].x * v[i].x + v[i].y * v[i].y + v[i].z * v[i].z + v[i].w * v[i].w;
;     ss = wave_sum(ss);
;     const float rs = rsqrtf(ss * (1.0f / 1024.0f) + EPS);
; #pragma unroll
;     for (int i = 0; i < 4; ++i) {
;       const float4 g = *(const float4*)(gain + i * 256 + lane * 4);
;       uint2 w; w.x = pk_bf16(v[i].x * rs * g.x, v[i].y * rs * g.y); w.y = pk_bf16(v[i].z * rs * g.z, v[i].w * rs * g.w);
;       *(uint2*)(xn + (size_t)r * 1024 + i * 256 + lane * 4) = w;
;     }
.LBB0_1016:
	s_andn2_saveexec_b64 s[0:1], s[0:1]
	v_lshl_add_u32 v0, v2, 4, v7
	v_ashrrev_i32_e32 v1, 31, v0
	v_mov_b64_e32 v[4:5], s[14:15]
	s_or_b64 exec, exec, s[0:1]
	v_lshlrev_b64 v[0:1], 12, v[0:1]
	v_lshlrev_b32_e32 v2, 2, v6
	v_lshl_add_u64 v[0:1], v[4:5], 0, v[0:1]
	v_and_b32_e32 v4, 0xfc, v2
	v_lshlrev_b32_e32 v8, 2, v4
	v_mov_b32_e32 v9, v130
	v_lshl_add_u64 v[0:1], v[0:1], 0, v[8:9]
	global_load_dwordx4 v[20:23], v[0:1], off offset:3072
	global_load_dwordx4 v[24:27], v[0:1], off offset:2048
	global_load_dwordx4 v[28:31], v[0:1], off offset:1024
	global_load_dwordx4 v[32:35], v[0:1], off
	v_readlane_b32 s36, v253, 8
	v_readlane_b32 s50, v253, 22
	v_readlane_b32 s51, v253, 23
	v_cmp_lt_i32_e32 vcc, v185, v184
	s_mov_b64 s[18:19], s[50:51]
	v_readlane_b32 s0, v254, 18
	v_cndmask_b32_e32 v5, v183, v185, vcc
	v_cmp_lt_i32_e32 vcc, v186, v184
	global_load_dwordx4 v[0:3], v8, s[50:51]
	v_lshlrev_b32_e32 v56, 2, v5
	v_cndmask_b32_e32 v5, v183, v186, vcc
	v_cmp_lt_i32_e32 vcc, v187, v184
	v_lshlrev_b32_e32 v57, 2, v5
	v_readlane_b32 s4, v253, 2
	v_cndmask_b32_e32 v5, v183, v187, vcc
	v_cmp_lt_i32_e32 vcc, v191, v184
	v_lshlrev_b32_e32 v58, 2, v5
	v_lshl_add_u64 v[36:37], s[18:19], 0, v[8:9]
	global_load_dwordx4 v[112:115], v[36:37], off offset:1024
	global_load_dwordx4 v[116:119], v[36:37], off offset:2048
	global_load_dwordx4 v[120:123], v[36:37], off offset:3072
	v_cndmask_b32_e32 v5, v183, v191, vcc
	v_cmp_lt_i32_e32 vcc, v192, v184
	v_lshlrev_b32_e32 v59, 2, v5
	v_lshlrev_b32_e32 v8, 1, v4
	v_cndmask_b32_e32 v5, v183, v192, vcc
	v_cmp_lt_i32_e32 vcc, v190, v184
	v_lshlrev_b32_e32 v60, 2, v5
	v_readlane_b32 s1, v254, 19
	v_cndmask_b32_e32 v5, v183, v190, vcc
	v_lshlrev_b32_e32 v61, 2, v5
	v_and_b32_e32 v5, 63, v6
	v_lshlrev_b32_e32 v6, 4, v5
	v_mov_b32_e32 v7, v130
	v_readlane_b32 s5, v253, 3
	v_readlane_b32 s6, v253, 4
	v_readlane_b32 s7, v253, 5
	v_lshl_add_u64 v[38:39], s[0:1], 0, v[8:9]
	v_add_u32_e32 v42, 0xffff8000, v46
	v_lshl_add_u64 v[40:41], s[6:7], 0, v[6:7]
	s_mov_b64 s[4:5], 0
	v_lshlrev_b32_e32 v44, 2, v4
	v_readlane_b32 s37, v253, 9
	v_readlane_b32 s38, v253, 10
	v_readlane_b32 s39, v253, 11
	v_readlane_b32 s40, v253, 12
	v_readlane_b32 s41, v253, 13
	v_readlane_b32 s42, v253, 14
	v_readlane_b32 s43, v253, 15
	v_readlane_b32 s44, v253, 16
	v_readlane_b32 s45, v253, 17
	v_readlane_b32 s46, v253, 18
	v_readlane_b32 s47, v253, 19
	v_readlane_b32 s48, v253, 20
	v_readlane_b32 s49, v253, 21
	s_branch .LBB0_1020
.LBB0_1019:
	s_or_b64 exec, exec, s[0:1]
	v_mov_b32_e32 v48, v28
	v_mov_b32_e32 v49, v32
	v_pk_mul_f32 v[48:49], v[48:49], v[48:49]
	v_mov_b32_e32 v50, v29
	v_mov_b32_e32 v51, v33
	v_pk_fma_f32 v[48:49], v[50:51], v[50:51], v[48:49]
	v_mov_b32_e32 v50, v30
	v_mov_b32_e32 v51, v34
	v_pk_fma_f32 v[48:49], v[50:51], v[50:51], v[48:49]
	v_mov_b32_e32 v50, v31
	v_mov_b32_e32 v51, v35
	v_pk_fma_f32 v[48:49], v[50:51], v[50:51], v[48:49]
	v_mov_b32_e32 v50, v20
	v_mov_b32_e32 v51, v24
	v_pk_mul_f32 v[50:51], v[50:51], v[50:51]
	v_mov_b32_e32 v52, v21
	v_mov_b32_e32 v53, v25
	v_pk_fma_f32 v[50:51], v[52:53], v[52:53], v[50:51]
	v_mov_b32_e32 v52, v22
	v_mov_b32_e32 v53, v26
	v_pk_fma_f32 v[50:51], v[52:53], v[52:53], v[50:51]
	v_mov_b32_e32 v52, v23
	v_mov_b32_e32 v53, v27
	v_pk_fma_f32 v[50:51], v[52:53], v[52:53], v[50:51]
	v_add_f32_e32 v43, v48, v49
	v_add_f32_e32 v43, v51, v43
	v_add_f32_e32 v43, v50, v43
	ds_bpermute_b32 v45, v56, v43
	v_ashrrev_i32_e32 v47, 31, v46
	v_lshlrev_b64 v[46:47], 11, v[46:47]
	v_lshl_add_u64 v[46:47], v[38:39], 0, v[46:47]
	v_add_u32_e32 v42, s80, v42
	s_waitcnt lgkmcnt(0)
	v_add_f32_e32 v43, v43, v45
	ds_bpermute_b32 v45, v57, v43
	s_waitcnt lgkmcnt(0)
	v_add_f32_e32 v43, v43, v45
	ds_bpermute_b32 v45, v58, v43
	s_waitcnt lgkmcnt(0)
	v_add_f32_e32 v43, v43, v45
	ds_bpermute_b32 v45, v59, v43
	s_waitcnt lgkmcnt(0)
	v_add_f32_e32 v43, v43, v45
	ds_bpermute_b32 v45, v60, v43
	s_waitcnt lgkmcnt(0)
	v_add_f32_e32 v43, v43, v45
	ds_bpermute_b32 v45, v61, v43
	s_waitcnt lgkmcnt(0)
	v_add_f32_e32 v43, v43, v45
	v_fmamk_f32 v43, v43, 0x3a800000, v132
	v_cmp_gt_f32_e32 vcc, s82, v43
	v_mul_f32_e32 v45, 0x4b800000, v43
	s_nop 0
	v_cndmask_b32_e32 v43, v43, v45, vcc
	v_rsq_f32_e32 v43, v43
	s_nop 0
	v_mul_f32_e32 v45, 0x45800000, v43
	v_cndmask_b32_e32 v43, v43, v45, vcc
	v_mul_f32_e32 v32, v32, v43
	v_mul_f32_e32 v33, v33, v43
	s_waitcnt vmcnt(0)
	v_mul_f32_e32 v32, v0, v32
	v_mul_f32_e32 v33, v1, v33
	v_cvt_pk_bf16_f32 v32, v32, v33
	v_mul_f32_e32 v33, v34, v43
	v_mul_f32_e32 v33, v2, v33
	v_mul_f32_e32 v34, v35, v43
	v_mul_f32_e32 v34, v3, v34
	v_cvt_pk_bf16_f32 v33, v33, v34
	global_store_dwordx2 v[46:47], v[32:33], off
	v_mul_f32_e32 v28, v28, v43
	v_mul_f32_e32 v29, v29, v43
	v_mul_f32_e32 v24, v24, v43
	v_mul_f32_e32 v25, v25, v43
	v_mul_f32_e32 v20, v20, v43
	v_mul_f32_e32 v21, v21, v43
	v_mov_b64_e32 v[32:33], v[112:113]
	v_mov_b64_e32 v[34:35], v[114:115]
	v_mul_f32_e32 v28, v32, v28
	v_mul_f32_e32 v29, v33, v29
	v_cvt_pk_bf16_f32 v28, v28, v29
	v_mul_f32_e32 v29, v30, v43
	v_mul_f32_e32 v29, v34, v29
	v_mul_f32_e32 v30, v31, v43
	v_mul_f32_e32 v30, v35, v30
	v_cvt_pk_bf16_f32 v29, v29, v30
	global_store_dwordx2 v[46:47], v[28:29], off offset:512
	v_mov_b64_e32 v[34:35], v[6:7]
	v_mov_b64_e32 v[32:33], v[4:5]
	v_mov_b64_e32 v[28:29], v[116:117]
	v_mov_b64_e32 v[30:31], v[118:119]
	v_mul_f32_e32 v24, v28, v24
	v_mul_f32_e32 v25, v29, v25
	v_cvt_pk_bf16_f32 v24, v24, v25
	v_mul_f32_e32 v25, v26, v43
	v_mul_f32_e32 v25, v30, v25
	v_mul_f32_e32 v26, v27, v43
	v_mul_f32_e32 v26, v26, v31
	v_cvt_pk_bf16_f32 v25, v25, v26
	global_store_dwordx2 v[46:47], v[24:25], off offset:1024
	v_mov_b64_e32 v[30:31], v[10:11]
	v_mov_b64_e32 v[28:29], v[8:9]
	v_mov_b64_e32 v[24:25], v[120:121]
	v_mov_b64_e32 v[26:27], v[122:123]
	v_mul_f32_e32 v20, v20, v24
	v_mul_f32_e32 v21, v21, v25
	v_cvt_pk_bf16_f32 v20, v20, v21
	v_mul_f32_e32 v21, v22, v43
	v_mul_f32_e32 v21, v21, v26
	v_mul_f32_e32 v22, v23, v43
	v_mul_f32_e32 v22, v22, v27
	v_cvt_pk_bf16_f32 v21, v21, v22
	global_store_dwordx2 v[46:47], v[20:21], off offset:1536
	v_mov_b32_e32 v46, v62
	v_mov_b64_e32 v[22:23], v[18:19]
	v_mov_b64_e32 v[20:21], v[16:17]
	v_mov_b64_e32 v[26:27], v[14:15]
	v_mov_b64_e32 v[24:25], v[12:13]
	s_andn2_b64 exec, exec, s[4:5]
	s_cbranch_execz .LBB0_1034

; __device__ __forceinline__ void norm_phase(const Params& p, const float* __restrict__ gain, int mode, int nslab) {
;     ...
;     if (nslab > 0 && r >= 32768) {
;       const float* sl = (const float*)(p.ws + OFF_SLAB) + (size_t)(r - 32768) * 1024 + lane * 4;
;       for (int sI = 0; sI < nslab; ++sI)
; #pragma unroll
;         for (int i = 0; i < 4; ++i) { const float4 a = *(const float4*)(sl + (size_t)sI * 131072 + i * 256); v[i].x += a.x; v[i].y += a.y; v[i].z += a.z; v[i].w += a.w; }
; #pragma unroll
;       for (int i = 0; i < 4; ++i) *(float4*)(hp + i * 256 + lane * 4) = v[i];
.LBB0_1032:
	v_lshl_add_u64 v[54:55], v[52:53], 0, s[6:7]
	s_add_u32 s6, s6, 0x200000
	s_addc_u32 s7, s7, 0
	v_add_co_u32_e32 v108, vcc, 0x1bb15000, v54
	s_nop 1
	v_addc_co_u32_e32 v109, vcc, 0, v55, vcc
	global_load_dwordx4 v[64:67], v[108:109], off offset:2304
	global_load_dwordx4 v[68:71], v[108:109], off offset:3328
	v_add_co_u32_e32 v108, vcc, 0x1bb16000, v54
	s_nop 1
	v_addc_co_u32_e32 v109, vcc, 0, v55, vcc
	global_load_dwordx4 v[72:75], v[108:109], off offset:256
	global_load_dwordx4 v[76:79], v[108:109], off offset:1280
	v_add_co_u32_e32 v108, vcc, 0x1bb95000, v54
	s_nop 1
	v_addc_co_u32_e32 v109, vcc, 0, v55, vcc
	global_load_dwordx4 v[80:83], v[108:109], off offset:2304
	global_load_dwordx4 v[84:87], v[108:109], off offset:3328
	v_add_co_u32_e32 v108, vcc, 0x1bb96000, v54
	s_nop 1
	v_addc_co_u32_e32 v109, vcc, 0, v55, vcc
	global_load_dwordx4 v[88:91], v[108:109], off offset:256
	global_load_dwordx4 v[92:95], v[108:109], off offset:1280
	v_add_co_u32_e32 v108, vcc, 0x1bc15000, v54
	s_nop 1
	v_addc_co_u32_e32 v109, vcc, 0, v55, vcc
	global_load_dwordx4 v[96:99], v[108:109], off offset:2304
	global_load_dwordx4 v[100:103], v[108:109], off offset:3328
	v_add_co_u32_e32 v108, vcc, 0x1bc16000, v54
	s_nop 1
	v_addc_co_u32_e32 v109, vcc, 0, v55, vcc
	global_load_dwordx4 v[104:107], v[108:109], off offset:256
	s_waitcnt vmcnt(10)
	v_pk_add_f32 v[32:33], v[32:33], v[64:65]
	v_pk_add_f32 v[34:35], v[34:35], v[66:67]
	global_load_dwordx4 v[64:67], v[108:109], off offset:1280
	s_waitcnt vmcnt(10)
	v_pk_add_f32 v[28:29], v[28:29], v[68:69]
	v_pk_add_f32 v[30:31], v[30:31], v[70:71]
	v_add_co_u32_e32 v108, vcc, 0x1bc95000, v54
	s_nop 1
	v_addc_co_u32_e32 v109, vcc, 0, v55, vcc
	global_load_dwordx4 v[68:71], v[108:109], off offset:2304
	s_waitcnt vmcnt(10)
	v_pk_add_f32 v[24:25], v[24:25], v[72:73]
	v_pk_add_f32 v[26:27], v[26:27], v[74:75]
	global_load_dwordx4 v[72:75], v[108:109], off offset:3328
	s_waitcnt vmcnt(10)
	v_pk_add_f32 v[20:21], v[20:21], v[76:77]
	v_pk_add_f32 v[22:23], v[22:23], v[78:79]
	v_add_co_u32_e32 v108, vcc, 0x1bc96000, v54
	s_nop 1
	v_addc_co_u32_e32 v109, vcc, 0, v55, vcc
	global_load_dwordx4 v[76:79], v[108:109], off offset:256
	s_waitcnt vmcnt(10)
	v_pk_add_f32 v[32:33], v[32:33], v[80:81]
	v_pk_add_f32 v[34:35], v[34:35], v[82:83]
	global_load_dwordx4 v[80:83], v[108:109], off offset:1280
	s_waitcnt vmcnt(10)
	v_pk_add_f32 v[28:29], v[28:29], v[84:85]
	v_pk_add_f32 v[30:31], v[30:31], v[86:87]
	s_waitcnt vmcnt(9)
	v_pk_add_f32 v[24:25], v[24:25], v[88:89]
	v_pk_add_f32 v[26:27], v[26:27], v[90:91]
	s_waitcnt vmcnt(8)
	v_pk_add_f32 v[20:21], v[20:21], v[92:93]
	v_pk_add_f32 v[22:23], v[22:23], v[94:95]
	s_waitcnt vmcnt(7)
	v_pk_add_f32 v[32:33], v[32:33], v[96:97]
	v_pk_add_f32 v[34:35], v[34:35], v[98:99]
	s_waitcnt vmcnt(6)
	v_pk_add_f32 v[28:29], v[28:29], v[100:101]
	v_pk_add_f32 v[30:31], v[30:31], v[102:103]
	s_waitcnt vmcnt(5)
	v_pk_add_f32 v[24:25], v[24:25], v[104:105]
	v_pk_add_f32 v[26:27], v[26:27], v[106:107]
	s_waitcnt vmcnt(4)
	v_pk_add_f32 v[20:21], v[20:21], v[64:65]
	v_pk_add_f32 v[22:23], v[22:23], v[66:67]
	s_waitcnt vmcnt(3)
	v_pk_add_f32 v[32:33], v[32:33], v[68:69]
	v_pk_add_f32 v[34:35], v[34:35], v[70:71]
	s_waitcnt vmcnt(2)
	v_pk_add_f32 v[28:29], v[28:29], v[72:73]
	v_pk_add_f32 v[30:31], v[30:31], v[74:75]
	s_waitcnt vmcnt(1)
	v_pk_add_f32 v[24:25], v[24:25], v[76:77]
	v_pk_add_f32 v[26:27], v[26:27], v[78:79]
	s_waitcnt vmcnt(0)
	v_pk_add_f32 v[20:21], v[20:21], v[80:81]
	v_pk_add_f32 v[22:23], v[22:23], v[82:83]
	s_cmp_eq_u32 s6, 0x800000
	s_cbranch_scc0 .LBB0_1032
	v_lshlrev_b64 v[48:49], 12, v[48:49]
	v_lshl_add_u64 v[48:49], v[50:51], 0, v[48:49]
	v_mov_b32_e32 v45, v130
	v_lshl_add_u64 v[48:49], v[48:49], 0, v[44:45]
	global_store_dwordx4 v[48:49], v[32:35], off
	global_store_dwordx4 v[48:49], v[28:31], off offset:1024
	global_store_dwordx4 v[48:49], v[24:27], off offset:2048
	global_store_dwordx4 v[48:49], v[20:23], off offset:3072
	s_branch .LBB0_1019

; DEVI unsigned pk_bf16(float lo, float hi) { unsigned r; asm("v_cvt_pk_bf16_f32 %0, %1, %2" : "=v"(r) : "v"(lo), "v"(hi)); return r; }
; DEVI float wave_sum(float v) { for (int o = 32; o; o >>= 1) v += __shfl_xor(v, o); return v; }
; __device__ __forceinline__ void norm_phase(const Params& p, const float* __restrict__ gain, int mode, int nslab) {
;     ...
;   if (wave < M) { const float* src = srcrow(wave);
; #pragma unroll
;     for (int i = 0; i < 4; ++i) vn[i] = *(const float4*)(src + i * 256 + lane * 4); }
;   for (int r = wave; r < M; r += nw) {
;     float* hp = hrow(p, r);
; #pragma unroll
;     for (int i = 0; i < 4; ++i) v[i] = vn[i];
;     if (r + nw < M) { const float* src = srcrow(r + nw);
; #pragma unroll
;       for (int i = 0; i < 4; ++i) vn[i] = *(const float4*)(src + i * 256 + lane * 4); }
;     if (nslab > 0 && r >= 32768) {
;       const float* sl = (const float*)(p.ws + OFF_SLAB) + (size_t)(r - 32768) * 1024 + lane * 4;
;       for (int sI = 0; sI < nslab; ++sI)
; #pragma unroll
;         for (int i = 0; i < 4; ++i) { const float4 a = *(const float4*)(sl + (size_t)sI * 131072 + i * 256); v[i].x += a.x; v[i].y += a.y; v[i].z += a.z; v[i].w += a.w; }
; #pragma unroll
;       for (int i = 0; i < 4; ++i) *(float4*)(hp + i * 256 + lane * 4) = v[i];
;     }
;     float ss = 0.f;
; #pragma unroll
;     for (int i = 0; i < 4; ++i) ss += v[i].x * v[i].x + v[i].y * v[i].y + v[i].z * v[i].z + v[i].w * v[i].w;
;     ss = wave_sum(ss);
;     const float rs = rsqrtf(ss * (1.0f / 1024.0f) + EPS);
; #pragma unroll
;     for (int i = 0; i < 4; ++i) {
;       const float4 g = *(const float4*)(gain + i * 256 + lane * 4);
;       uint2 w; w.x = pk_bf16(v[i].x * rs * g.x, v[i].y * rs * g.y); w.y = pk_bf16(v[i].z * rs * g.z, v[i].w * rs * g.w);
;       *(uint2*)(xn + (size_t)r * 1024 + i * 256 + lane * 4) = w;
;     }
.LBB0_2090:
	s_or_b64 exec, exec, s[0:1]
	v_readlane_b32 s0, v255, 4
	v_lshlrev_b64 v[0:1], 12, v[0:1]
	v_readlane_b32 s1, v255, 5
	v_lshl_add_u64 v[0:1], v[2:3], 0, v[0:1]
	v_lshlrev_b32_e32 v2, 2, v12
	s_mov_b32 s5, s1
	s_lshl_b32 s4, s56, 10
	v_writelane_b32 v255, s0, 4
	v_readlane_b32 s36, v253, 44
	v_and_b32_e32 v36, 0xfc, v2
	v_writelane_b32 v255, s1, 5
	s_lshl_b64 s[0:1], s[4:5], 2
	v_readlane_b32 s46, v253, 54
	v_lshlrev_b32_e32 v14, 2, v36
	v_mov_b32_e32 v15, v130
	v_readlane_b32 s47, v253, 55
	s_add_u32 s0, s46, s0
	v_lshl_add_u64 v[4:5], v[0:1], 0, v[14:15]
	s_addc_u32 s1, s47, s1
	global_load_dwordx4 v[0:3], v[4:5], off offset:3072
	global_load_dwordx4 v[8:11], v[4:5], off offset:2048
	global_load_dwordx4 v[28:31], v[4:5], off offset:1024
	global_load_dwordx4 v[32:35], v[4:5], off
	s_nop 0
	global_load_dwordx4 v[4:7], v14, s[0:1]
	v_cmp_lt_i32_e32 vcc, v185, v184
	v_lshl_add_u64 v[38:39], s[0:1], 0, v[14:15]
	global_load_dwordx4 v[112:115], v[38:39], off offset:1024
	global_load_dwordx4 v[116:119], v[38:39], off offset:2048
	global_load_dwordx4 v[120:123], v[38:39], off offset:3072
	v_readlane_b32 s0, v254, 18
	v_cndmask_b32_e32 v13, v183, v185, vcc
	v_cmp_lt_i32_e32 vcc, v186, v184
	v_lshlrev_b32_e32 v37, 2, v13
	v_lshlrev_b32_e32 v14, 1, v36
	v_cndmask_b32_e32 v13, v183, v186, vcc
	v_cmp_lt_i32_e32 vcc, v187, v184
	v_lshlrev_b32_e32 v54, 2, v13
	v_readlane_b32 s1, v254, 19
	v_cndmask_b32_e32 v13, v183, v187, vcc
	v_cmp_lt_i32_e32 vcc, v191, v184
	v_lshlrev_b32_e32 v55, 2, v13
	v_lshl_add_u64 v[40:41], s[0:1], 0, v[14:15]
	v_cndmask_b32_e32 v13, v183, v191, vcc
	v_cmp_lt_i32_e32 vcc, v192, v184
	v_lshlrev_b32_e32 v56, 2, v13
	v_and_b32_e32 v12, 63, v12
	v_cndmask_b32_e32 v13, v183, v192, vcc
	v_cmp_lt_i32_e32 vcc, v190, v184
	v_lshlrev_b32_e32 v57, 2, v13
	v_readlane_b32 s0, v254, 25
	v_cndmask_b32_e32 v13, v183, v190, vcc
	s_and_b64 s[4:5], s[16:17], exec
	v_lshlrev_b32_e32 v58, 2, v13
	v_lshlrev_b32_e32 v12, 4, v12
	v_mov_b32_e32 v13, v130
	v_readlane_b32 s1, v254, 26
	s_cselect_b32 s18, 8, 4
	v_add_u32_e32 v44, 0xffff8000, v46
	v_lshl_add_u64 v[42:43], s[0:1], 0, v[12:13]
	s_mov_b64 s[4:5], 0
	v_readlane_b32 s37, v253, 45
	v_readlane_b32 s38, v253, 46
	v_readlane_b32 s39, v253, 47
	v_readlane_b32 s40, v253, 48
	v_readlane_b32 s41, v253, 49
	v_readlane_b32 s42, v253, 50
	v_readlane_b32 s43, v253, 51
	v_readlane_b32 s44, v253, 52
	v_readlane_b32 s45, v253, 53
	v_readlane_b32 s48, v253, 56
	v_readlane_b32 s49, v253, 57
	v_readlane_b32 s50, v253, 58
	v_readlane_b32 s51, v253, 59
	s_branch .LBB0_2092
.LBB0_2091:
	s_or_b64 exec, exec, s[0:1]
	v_mov_b32_e32 v48, v28
	v_mov_b32_e32 v49, v32
	v_pk_mul_f32 v[48:49], v[48:49], v[48:49]
	v_mov_b32_e32 v50, v29
	v_mov_b32_e32 v51, v33
	v_pk_fma_f32 v[48:49], v[50:51], v[50:51], v[48:49]
	v_mov_b32_e32 v50, v30
	v_mov_b32_e32 v51, v34
	v_pk_fma_f32 v[48:49], v[50:51], v[50:51], v[48:49]
	v_mov_b32_e32 v50, v31
	v_mov_b32_e32 v51, v35
	v_pk_fma_f32 v[48:49], v[50:51], v[50:51], v[48:49]
	v_mov_b32_e32 v50, v0
	v_mov_b32_e32 v51, v8
	v_pk_mul_f32 v[50:51], v[50:51], v[50:51]
	v_mov_b32_e32 v52, v1
	v_mov_b32_e32 v53, v9
	v_pk_fma_f32 v[50:51], v[52:53], v[52:53], v[50:51]
	v_mov_b32_e32 v52, v2
	v_mov_b32_e32 v53, v10
	v_pk_fma_f32 v[50:51], v[52:53], v[52:53], v[50:51]
	v_mov_b32_e32 v52, v3
	v_mov_b32_e32 v53, v11
	v_pk_fma_f32 v[50:51], v[52:53], v[52:53], v[50:51]
	v_add_f32_e32 v45, v48, v49
	v_add_f32_e32 v45, v51, v45
	v_add_f32_e32 v45, v50, v45
	ds_bpermute_b32 v47, v37, v45
	v_add_u32_e32 v44, s80, v44
	s_waitcnt lgkmcnt(0)
	v_add_f32_e32 v45, v45, v47
	ds_bpermute_b32 v47, v54, v45
	s_waitcnt lgkmcnt(0)
	v_add_f32_e32 v45, v45, v47
	ds_bpermute_b32 v47, v55, v45
	s_waitcnt lgkmcnt(0)
	v_add_f32_e32 v45, v45, v47
	ds_bpermute_b32 v47, v56, v45
	s_waitcnt lgkmcnt(0)
	v_add_f32_e32 v45, v45, v47
	ds_bpermute_b32 v47, v57, v45
	s_waitcnt lgkmcnt(0)
	v_add_f32_e32 v45, v45, v47
	ds_bpermute_b32 v47, v58, v45
	s_waitcnt lgkmcnt(0)
	v_add_f32_e32 v45, v45, v47
	v_fmamk_f32 v45, v45, 0x3a800000, v132
	v_cmp_gt_f32_e32 vcc, s25, v45
	v_mul_f32_e32 v47, 0x4b800000, v45
	s_nop 0
	v_cndmask_b32_e32 v45, v45, v47, vcc
	v_rsq_f32_e32 v45, v45
	s_nop 0
	v_mul_f32_e32 v47, 0x45800000, v45
	v_cndmask_b32_e32 v45, v45, v47, vcc
	v_mul_f32_e32 v32, v32, v45
	v_mul_f32_e32 v33, v33, v45
	s_waitcnt vmcnt(0)
	v_mul_f32_e32 v32, v4, v32
	v_mul_f32_e32 v33, v5, v33
	v_ashrrev_i32_e32 v47, 31, v46
	v_cvt_pk_bf16_f32 v32, v32, v33
	v_mul_f32_e32 v33, v34, v45
	v_lshlrev_b64 v[46:47], 11, v[46:47]
	v_mul_f32_e32 v33, v6, v33
	v_mul_f32_e32 v34, v35, v45
	v_lshl_add_u64 v[46:47], v[40:41], 0, v[46:47]
	v_mul_f32_e32 v34, v7, v34
	v_cvt_pk_bf16_f32 v33, v33, v34
	global_store_dwordx2 v[46:47], v[32:33], off
	v_mul_f32_e32 v28, v28, v45
	v_mul_f32_e32 v29, v29, v45
	v_mul_f32_e32 v8, v8, v45
	v_mul_f32_e32 v9, v9, v45
	v_mul_f32_e32 v0, v0, v45
	v_mul_f32_e32 v1, v1, v45
	v_mov_b64_e32 v[32:33], v[112:113]
	v_mov_b64_e32 v[34:35], v[114:115]
	v_mul_f32_e32 v28, v32, v28
	v_mul_f32_e32 v29, v33, v29
	v_cvt_pk_bf16_f32 v28, v28, v29
	v_mul_f32_e32 v29, v30, v45
	v_mul_f32_e32 v29, v34, v29
	v_mul_f32_e32 v30, v31, v45
	v_mul_f32_e32 v30, v35, v30
	v_cvt_pk_bf16_f32 v29, v29, v30
	global_store_dwordx2 v[46:47], v[28:29], off offset:512
	v_mov_b64_e32 v[34:35], v[14:15]
	v_mov_b64_e32 v[32:33], v[12:13]
	v_mov_b64_e32 v[28:29], v[116:117]
	v_mov_b64_e32 v[30:31], v[118:119]
	v_mul_f32_e32 v8, v28, v8
	v_mul_f32_e32 v9, v29, v9
	v_cvt_pk_bf16_f32 v8, v8, v9
	v_mul_f32_e32 v9, v10, v45
	v_mul_f32_e32 v9, v30, v9
	v_mul_f32_e32 v10, v11, v45
	v_mul_f32_e32 v10, v10, v31
	v_cvt_pk_bf16_f32 v9, v9, v10
	global_store_dwordx2 v[46:47], v[8:9], off offset:1024
	v_mov_b64_e32 v[30:31], v[18:19]
	v_mov_b64_e32 v[28:29], v[16:17]
	v_mov_b64_e32 v[8:9], v[120:121]
	v_mov_b64_e32 v[10:11], v[122:123]
	v_mul_f32_e32 v0, v0, v8
	v_mul_f32_e32 v1, v1, v9
	v_cvt_pk_bf16_f32 v0, v0, v1
	v_mul_f32_e32 v1, v2, v45
	v_mul_f32_e32 v1, v1, v10
	v_mul_f32_e32 v2, v3, v45
	v_mul_f32_e32 v2, v2, v11
	v_cvt_pk_bf16_f32 v1, v1, v2
	global_store_dwordx2 v[46:47], v[0:1], off offset:1536
	v_mov_b32_e32 v46, v59
	v_mov_b64_e32 v[2:3], v[26:27]
	v_mov_b64_e32 v[0:1], v[24:25]
	v_mov_b64_e32 v[10:11], v[22:23]
	v_mov_b64_e32 v[8:9], v[20:21]
	s_andn2_b64 exec, exec, s[4:5]
	s_cbranch_execz .LBB0_2114

; __device__ __forceinline__ void norm_phase(const Params& p, const float* __restrict__ gain, int mode, int nslab) {
;     ...
;     if (nslab > 0 && r >= 32768) {
;       const float* sl = (const float*)(p.ws + OFF_SLAB) + (size_t)(r - 32768) * 1024 + lane * 4;
;       for (int sI = 0; sI < nslab; ++sI)
; #pragma unroll
;         for (int i = 0; i < 4; ++i) { const float4 a = *(const float4*)(sl + (size_t)sI * 131072 + i * 256); v[i].x += a.x; v[i].y += a.y; v[i].z += a.z; v[i].w += a.w; }
; #pragma unroll
;       for (int i = 0; i < 4; ++i) *(float4*)(hp + i * 256 + lane * 4) = v[i];
.Lmn_loop4:
	global_load_dwordx4 v[64:67], v[52:53], off
	global_load_dwordx4 v[68:71], v[52:53], off offset:1024
	global_load_dwordx4 v[72:75], v[52:53], off offset:2048
	global_load_dwordx4 v[76:79], v[52:53], off offset:3072
	v_lshl_add_u64 v[52:53], v[52:53], 0, s[10:11]
	global_load_dwordx4 v[80:83], v[52:53], off
	global_load_dwordx4 v[84:87], v[52:53], off offset:1024
	global_load_dwordx4 v[88:91], v[52:53], off offset:2048
	global_load_dwordx4 v[92:95], v[52:53], off offset:3072
	v_lshl_add_u64 v[52:53], v[52:53], 0, s[10:11]
	global_load_dwordx4 v[96:99], v[52:53], off
	global_load_dwordx4 v[100:103], v[52:53], off offset:1024
	global_load_dwordx4 v[104:107], v[52:53], off offset:2048
	global_load_dwordx4 v[108:111], v[52:53], off offset:3072
	s_waitcnt vmcnt(11)
	v_pk_add_f32 v[32:33], v[32:33], v[64:65]
	v_pk_add_f32 v[34:35], v[34:35], v[66:67]
	v_lshl_add_u64 v[52:53], v[52:53], 0, s[10:11]
	global_load_dwordx4 v[64:67], v[52:53], off
	s_waitcnt vmcnt(11)
	v_pk_add_f32 v[28:29], v[28:29], v[68:69]
	v_pk_add_f32 v[30:31], v[30:31], v[70:71]
	global_load_dwordx4 v[68:71], v[52:53], off offset:1024
	s_waitcnt vmcnt(11)
	v_pk_add_f32 v[8:9], v[8:9], v[72:73]
	v_pk_add_f32 v[10:11], v[10:11], v[74:75]
	global_load_dwordx4 v[72:75], v[52:53], off offset:2048
	s_waitcnt vmcnt(11)
	v_pk_add_f32 v[0:1], v[0:1], v[76:77]
	v_pk_add_f32 v[2:3], v[2:3], v[78:79]
	global_load_dwordx4 v[76:79], v[52:53], off offset:3072
	s_waitcnt vmcnt(11)
	v_pk_add_f32 v[32:33], v[32:33], v[80:81]
	v_pk_add_f32 v[34:35], v[34:35], v[82:83]
	s_waitcnt vmcnt(10)
	v_pk_add_f32 v[28:29], v[28:29], v[84:85]
	v_pk_add_f32 v[30:31], v[30:31], v[86:87]
	s_waitcnt vmcnt(9)
	v_pk_add_f32 v[8:9], v[8:9], v[88:89]
	v_pk_add_f32 v[10:11], v[10:11], v[90:91]
	s_waitcnt vmcnt(8)
	v_pk_add_f32 v[0:1], v[0:1], v[92:93]
	v_pk_add_f32 v[2:3], v[2:3], v[94:95]
	s_waitcnt vmcnt(7)
	v_pk_add_f32 v[32:33], v[32:33], v[96:97]
	v_pk_add_f32 v[34:35], v[34:35], v[98:99]
	s_waitcnt vmcnt(6)
	v_pk_add_f32 v[28:29], v[28:29], v[100:101]
	v_pk_add_f32 v[30:31], v[30:31], v[102:103]
	s_waitcnt vmcnt(5)
	v_pk_add_f32 v[8:9], v[8:9], v[104:105]
	v_pk_add_f32 v[10:11], v[10:11], v[106:107]
	s_waitcnt vmcnt(4)
	v_pk_add_f32 v[0:1], v[0:1], v[108:109]
	v_pk_add_f32 v[2:3], v[2:3], v[110:111]
	s_waitcnt vmcnt(3)
	v_pk_add_f32 v[32:33], v[32:33], v[64:65]
	v_pk_add_f32 v[34:35], v[34:35], v[66:67]
	s_waitcnt vmcnt(2)
	v_pk_add_f32 v[28:29], v[28:29], v[68:69]
	v_pk_add_f32 v[30:31], v[30:31], v[70:71]
	s_waitcnt vmcnt(1)
	v_pk_add_f32 v[8:9], v[8:9], v[72:73]
	v_pk_add_f32 v[10:11], v[10:11], v[74:75]
	s_waitcnt vmcnt(0)
	v_pk_add_f32 v[0:1], v[0:1], v[76:77]
	v_pk_add_f32 v[2:3], v[2:3], v[78:79]
	v_lshl_add_u64 v[52:53], v[52:53], 0, s[10:11]
	s_add_i32 s8, s8, -4
	s_cmp_eq_u32 s8, 0
	s_cbranch_scc0 .Lmn_loop4
	s_branch .Lmn_done
